# plus attention P.V: the two key steps of one q-block accumulator issued consecutively in 10 of 16 dv-block groups per tile pair
# baseline (speedup 1.0000x reference)
.LBB0_963:
	s_add_u32 s36, s28, s30
	s_addc_u32 s37, s29, s31
	s_add_u32 s34, s36, 0x100000
	s_addc_u32 s35, s37, 0
	s_lshl_b32 s9, s19, 14
	s_add_i32 s48, s95, s9
	s_mov_b32 m0, s48
	s_nop 0
	global_load_lds_dwordx4 v228, s[34:35]
	s_add_i32 m0, s48, 0x400
	s_nop 0
	global_load_lds_dwordx4 v231, s[34:35]
	ds_read_b128 v[236:239], v196 offset:12288
	s_waitcnt lgkmcnt(0)
	v_mfma_f32_16x16x32_bf16 v[120:123], v[184:187], v[36:39], v[120:123]
	v_exp_f32_e32 v196, v132
	v_exp_f32_e32 v208, v133
	v_add_f32_e32 v206, v152, v206
	v_add_f32_e32 v207, v136, v207
	v_mfma_f32_16x16x32_bf16 v[124:127], v[184:187], v[0:3], v[124:127]
	v_add_u32_e32 v209, s25, v233
	ds_read_b128 v[184:187], v209
	v_exp_f32_e32 v210, v134
	v_exp_f32_e32 v211, v135
	v_mfma_f32_16x16x32_bf16 v[132:135], v[176:179], v[0:3], v[148:151]
	v_mfma_f32_16x16x32_bf16 v[160:163], v[176:179], v[36:39], v[160:163]
	s_nop 1
	v_add_f32_e32 v148, v153, v206
	v_add_f32_e32 v149, v137, v207
	ds_read_b128 v[176:179], v209 offset:4096
	v_mfma_f32_16x16x32_bf16 v[164:167], v[180:183], v[0:3], v[164:167]
	v_exp_f32_e32 v212, v128
	v_exp_f32_e32 v213, v129
	v_add_f32_e32 v148, v154, v148
	v_mfma_f32_16x16x32_bf16 v[168:171], v[180:183], v[36:39], v[168:171]
	v_add_f32_e32 v149, v138, v149
	ds_read_b128 v[180:183], v209 offset:8192
	v_exp_f32_e32 v219, v130
	v_exp_f32_e32 v235, v131
	v_mfma_f32_16x16x32_bf16 v[128:131], v[236:239], v[0:3], v[140:143]
	v_add_f32_e32 v148, v155, v148
	v_add_f32_e32 v149, v139, v149
	v_mfma_f32_16x16x32_bf16 v[140:143], v[236:239], v[36:39], v[172:175]
	s_nop 2
	ds_read_b128 v[172:175], v209 offset:12288
	s_waitcnt lgkmcnt(0)
	v_mfma_f32_16x16x32_bf16 v[120:123], v[184:187], v[28:31], v[120:123]
	v_add_f32_e32 v150, v188, v148
	v_add_f32_e32 v149, v190, v149
	v_mfma_f32_16x16x32_bf16 v[124:127], v[184:187], v[12:15], v[124:127]
	v_cvt_pk_bf16_f32 v148, v156, v157
	v_add_u32_e32 v206, s25, v230
	ds_read_b128 v[184:187], v206
	v_add_f32_e32 v150, v189, v150
	v_add_f32_e32 v151, v191, v149
	v_mfma_f32_16x16x32_bf16 v[132:135], v[176:179], v[12:15], v[132:135]
	v_cvt_pk_bf16_f32 v149, v158, v159
	v_mfma_f32_16x16x32_bf16 v[156:159], v[176:179], v[28:31], v[160:163]
	ds_read_b128 v[176:179], v206 offset:4096
	v_mfma_f32_16x16x32_bf16 v[162:165], v[180:183], v[12:15], v[164:167]
	s_nop 0
	v_add_f32_e32 v160, v194, v150
	v_add_f32_e32 v151, v192, v151
	v_mfma_f32_16x16x32_bf16 v[166:169], v[180:183], v[28:31], v[168:171]
	v_cvt_pk_bf16_f32 v150, v152, v153
	ds_read_b128 v[180:183], v206 offset:8192
	v_mfma_f32_16x16x32_bf16 v[128:131], v[172:175], v[12:15], v[128:131]
	v_add_f32_e32 v160, v195, v160
	v_add_f32_e32 v161, v193, v151
	v_mfma_f32_16x16x32_bf16 v[140:143], v[172:175], v[28:31], v[140:143]
	v_cvt_pk_bf16_f32 v151, v154, v155
	ds_read_b128 v[152:155], v206 offset:12288
	s_waitcnt lgkmcnt(0)
	v_mfma_f32_16x16x32_bf16 v[120:123], v[184:187], v[24:27], v[120:123]
	v_add_f32_e32 v174, v196, v160
	v_add_f32_e32 v161, v212, v161
	v_mfma_f32_16x16x32_bf16 v[124:127], v[184:187], v[8:11], v[124:127]
	v_cvt_pk_bf16_f32 v160, v144, v145
	v_add_u32_e32 v186, s25, v226
	ds_read_b128 v[170:173], v186 offset:16384
	v_add_f32_e32 v184, v208, v174
	v_add_f32_e32 v185, v213, v161
	v_mfma_f32_16x16x32_bf16 v[132:135], v[176:179], v[8:11], v[132:135]
	v_cvt_pk_bf16_f32 v161, v146, v147
	v_mfma_f32_16x16x32_bf16 v[144:147], v[176:179], v[24:27], v[156:159]
	s_nop 2
	ds_read_b128 v[156:159], v186 offset:18432
	v_mfma_f32_16x16x32_bf16 v[174:177], v[180:183], v[8:11], v[162:165]
	v_mfma_f32_16x16x32_bf16 v[178:181], v[180:183], v[24:27], v[166:169]
	s_nop 1
	v_add_f32_e32 v163, v210, v184
	v_add_f32_e32 v164, v219, v185
	v_cvt_pk_bf16_f32 v162, v136, v137
	ds_read_b128 v[182:185], v186 offset:20480
	v_add_f32_e32 v206, v211, v163
	v_add_f32_e32 v207, v235, v164
	v_mfma_f32_16x16x32_bf16 v[128:131], v[152:155], v[8:11], v[128:131]
	v_cvt_pk_bf16_f32 v163, v138, v139
	v_mfma_f32_16x16x32_bf16 v[136:139], v[152:155], v[24:27], v[140:143]
	s_nop 2
	ds_read_b128 v[140:143], v186 offset:22528
	s_waitcnt lgkmcnt(0)
	v_mfma_f32_16x16x32_bf16 v[120:123], v[170:173], v[32:35], v[120:123]
	v_cvt_pk_bf16_f32 v164, v188, v189
	v_mfma_f32_16x16x32_bf16 v[124:127], v[170:173], v[16:19], v[124:127]
	v_add_u32_e32 v152, s25, v224
	ds_read_b128 v[168:171], v152 offset:16384
	v_mfma_f32_16x16x32_bf16 v[132:135], v[156:159], v[16:19], v[132:135]
	v_cvt_pk_bf16_f32 v165, v194, v195
	v_mfma_f32_16x16x32_bf16 v[186:189], v[156:159], v[32:35], v[144:147]
	ds_read_b128 v[236:239], v152 offset:18432
	v_mfma_f32_16x16x32_bf16 v[240:243], v[182:185], v[16:19], v[174:177]
	v_cvt_pk_bf16_f32 v166, v196, v208
	v_mfma_f32_16x16x32_bf16 v[176:179], v[182:185], v[32:35], v[178:181]
	s_nop 2
	ds_read_b128 v[180:183], v152 offset:20480
	v_mfma_f32_16x16x32_bf16 v[128:131], v[140:143], v[16:19], v[128:131]
	v_cvt_pk_bf16_f32 v167, v210, v211
	v_mfma_f32_16x16x32_bf16 v[244:247], v[140:143], v[32:35], v[136:139]
	ds_read_b128 v[248:251], v152 offset:22528
	s_waitcnt lgkmcnt(0)
	v_mfma_f32_16x16x32_bf16 v[152:155], v[168:171], v[20:23], v[124:127]
	v_mfma_f32_16x16x32_bf16 v[144:147], v[168:171], v[44:47], v[120:123]
	v_cvt_pk_bf16_f32 v168, v190, v191
	v_mfma_f32_16x16x32_bf16 v[156:159], v[236:239], v[20:23], v[132:135]
	v_cvt_pk_bf16_f32 v169, v192, v193
	v_mfma_f32_16x16x32_bf16 v[172:175], v[236:239], v[44:47], v[186:189]
	v_mfma_f32_16x16x32_bf16 v[140:143], v[180:183], v[20:23], v[240:243]
	v_cvt_pk_bf16_f32 v170, v212, v213
	v_mfma_f32_16x16x32_bf16 v[136:139], v[180:183], v[44:47], v[176:179]
	v_mfma_f32_16x16x32_bf16 v[132:135], v[248:251], v[20:23], v[128:131]
	v_cvt_pk_bf16_f32 v171, v219, v235
	v_mfma_f32_16x16x32_bf16 v[128:131], v[248:251], v[44:47], v[244:247]
	s_lshl_b32 s34, s8, 14
	s_add_i32 s48, s34, 0
	s_add_i32 s48, s48, 0x12000
	v_add_u32_e32 v196, s48, v222
	v_add_u32_e32 v219, s48, v223
	ds_read_b64_tr_b16 v[120:121], v196
	ds_read_b64_tr_b16 v[122:123], v196 offset:4096
	ds_read_b64_tr_b16 v[124:125], v196 offset:8192
	ds_read_b64_tr_b16 v[126:127], v196 offset:12288
	ds_read_b64_tr_b16 v[176:177], v219
	ds_read_b64_tr_b16 v[178:179], v219 offset:4096
	ds_read_b64_tr_b16 v[182:183], v219 offset:4608
	ds_read_b64_tr_b16 v[180:181], v219 offset:512
	ds_read_b64_tr_b16 v[184:185], v219 offset:8192
	ds_read_b64_tr_b16 v[186:187], v219 offset:12288
	ds_read_b64_tr_b16 v[190:191], v219 offset:12800
	ds_read_b64_tr_b16 v[188:189], v219 offset:8704
	s_waitcnt lgkmcnt(0)
	v_mfma_f32_16x16x32_bf16 v[112:115], v[176:179], v[148:151], v[112:115]
	v_mfma_f32_16x16x32_bf16 v[116:119], v[176:179], v[160:163], v[116:119]
	v_max_f32_e32 v176, v153, v153
	v_max_f32_e32 v177, v152, v152
	v_max_f32_e32 v176, v177, v176
	v_mfma_f32_16x16x32_bf16 v[112:115], v[184:187], v[164:167], v[112:115]
	v_max3_f32 v176, v176, v154, v155
	v_max3_f32 v176, v176, v156, v157
	v_max3_f32 v208, v176, v158, v159
	v_mfma_f32_16x16x32_bf16 v[116:119], v[184:187], v[168:171], v[116:119]
	ds_read_b64_tr_b16 v[192:193], v196 offset:512
	ds_read_b64_tr_b16 v[194:195], v196 offset:4608
	ds_read_b64_tr_b16 v[236:237], v196 offset:8704
	ds_read_b64_tr_b16 v[238:239], v196 offset:12800
	v_mfma_f32_16x16x32_bf16 v[108:111], v[120:123], v[148:151], v[108:111]
	v_mfma_f32_16x16x32_bf16 v[176:179], v[120:123], v[160:163], v[104:107]
	v_mfma_f32_16x16x32_bf16 v[104:107], v[124:127], v[164:167], v[108:111]
	s_nop 5
	v_max3_f32 v108, v208, v140, v141
	v_max3_f32 v108, v108, v142, v143
	v_max3_f32 v108, v108, v132, v133
	v_max3_f32 v120, v108, v134, v135
	v_mfma_f32_16x16x32_bf16 v[108:111], v[124:127], v[168:171], v[176:179]
	ds_read_b64_tr_b16 v[184:185], v219 offset:1024
	ds_read_b64_tr_b16 v[186:187], v219 offset:5120
	s_nop 0
	ds_read_b64_tr_b16 v[176:177], v219 offset:9216
	ds_read_b64_tr_b16 v[178:179], v219 offset:13312
	v_mfma_f32_16x16x32_bf16 v[96:99], v[180:183], v[148:151], v[96:99]
	v_max_f32_e32 v121, v145, v145
	v_max_f32_e32 v122, v144, v144
	v_max_f32_e32 v121, v122, v121
	v_mfma_f32_16x16x32_bf16 v[96:99], v[188:191], v[164:167], v[96:99]
	v_max3_f32 v121, v121, v146, v147
	v_max3_f32 v121, v121, v172, v173
	v_max3_f32 v121, v121, v174, v175
	v_mfma_f32_16x16x32_bf16 v[100:103], v[180:183], v[160:163], v[100:103]
	v_mfma_f32_16x16x32_bf16 v[100:103], v[188:191], v[168:171], v[100:103]
	ds_read_b64_tr_b16 v[188:189], v196 offset:1024
	ds_read_b64_tr_b16 v[190:191], v196 offset:5120
	ds_read_b64_tr_b16 v[180:181], v196 offset:9216
	ds_read_b64_tr_b16 v[182:183], v196 offset:13312
	s_waitcnt lgkmcnt(0)
	v_mfma_f32_16x16x32_bf16 v[92:95], v[192:195], v[148:151], v[92:95]
	v_mfma_f32_16x16x32_bf16 v[122:125], v[192:195], v[160:163], v[88:91]
	v_mfma_f32_16x16x32_bf16 v[88:91], v[236:239], v[164:167], v[92:95]
	s_nop 5
	v_max3_f32 v92, v121, v136, v137
	v_max3_f32 v92, v92, v138, v139
	v_max3_f32 v92, v92, v128, v129
	v_max3_f32 v121, v92, v130, v131
	v_mfma_f32_16x16x32_bf16 v[92:95], v[236:239], v[168:171], v[122:125]
	s_nop 2
	v_max_f32_e32 v122, v120, v121
	v_cmp_ge_f32_e32 vcc, s62, v122
	s_cmp_lg_u64 vcc, exec
	s_cselect_b64 s[34:35], -1, 0
	s_cmp_eq_u64 vcc, exec
	s_cbranch_scc1 .LBB0_965
	ds_bpermute_b32 v48, v220, v120
	v_max_f32_e32 v49, v120, v120
	v_max_f32_e32 v50, v121, v121
	s_waitcnt lgkmcnt(0)
	v_max_f32_e32 v48, v48, v48
	v_max_f32_e32 v48, v49, v48
	ds_bpermute_b32 v49, v221, v48
	s_waitcnt lgkmcnt(0)
	v_max3_f32 v48, v48, v49, 0
	ds_bpermute_b32 v49, v220, v121
	v_exp_f32_e64 v208, -v48
	v_sub_f32_e32 v152, v152, v48
	v_sub_f32_e32 v153, v153, v48
	v_sub_f32_e32 v154, v154, v48
	s_waitcnt lgkmcnt(0)
	v_max_f32_e32 v49, v49, v49
	v_max_f32_e32 v49, v50, v49
	ds_bpermute_b32 v50, v221, v49
	v_sub_f32_e32 v155, v155, v48
	v_sub_f32_e32 v156, v156, v48
	v_sub_f32_e32 v157, v157, v48
	v_sub_f32_e32 v158, v158, v48
	s_waitcnt lgkmcnt(0)
	v_max3_f32 v49, v49, v50, 0
	v_exp_f32_e64 v209, -v49
	v_pk_add_f32 v[202:203], v[202:203], v[48:49]
	v_sub_f32_e32 v159, v159, v48
	v_pk_add_f32 v[120:121], v[202:203], 0 neg_lo:[1,1] neg_hi:[1,1]
	v_xor_b32_e32 v124, 0x80000000, v203
	v_sub_f32_e32 v143, v143, v48
	v_sub_f32_e32 v142, v142, v48
	v_sub_f32_e32 v141, v141, v48
	v_sub_f32_e32 v140, v140, v48
	v_sub_f32_e32 v135, v135, v48
	v_sub_f32_e32 v134, v134, v48
	v_sub_f32_e32 v133, v133, v48
	v_sub_f32_e32 v132, v132, v48
	v_mov_b32_e32 v121, v120
	v_mov_b32_e32 v122, v120
	v_mov_b32_e32 v123, v120
	v_sub_f32_e32 v144, v144, v49
	v_sub_f32_e32 v145, v145, v49
	v_sub_f32_e32 v146, v146, v49
	v_sub_f32_e32 v147, v147, v49
	v_sub_f32_e32 v172, v172, v49
	v_sub_f32_e32 v173, v173, v49
	v_sub_f32_e32 v174, v174, v49
	v_sub_f32_e32 v175, v175, v49
	v_sub_f32_e32 v139, v139, v49
	v_sub_f32_e32 v138, v138, v49
	v_sub_f32_e32 v137, v137, v49
	v_sub_f32_e32 v136, v136, v49
	v_sub_f32_e32 v131, v131, v49
	v_sub_f32_e32 v130, v130, v49
	v_sub_f32_e32 v129, v129, v49
	v_sub_f32_e32 v128, v128, v49
	v_mov_b32_e32 v125, v124
	v_mov_b32_e32 v126, v124
	v_mov_b32_e32 v127, v124
	v_mov_b32_e32 v48, v120
	v_mov_b32_e32 v49, v120
	v_mov_b32_e32 v50, v120
	v_mov_b32_e32 v51, v120
	v_mov_b32_e32 v52, v124
	v_mov_b32_e32 v53, v124
	v_mov_b32_e32 v54, v124
	v_mov_b32_e32 v55, v124
	s_branch .LBB0_966

.LBB0_966:
	ds_read_b64_tr_b16 v[192:193], v219 offset:1536
	ds_read_b64_tr_b16 v[194:195], v219 offset:5632
	ds_read_b64_tr_b16 v[236:237], v219 offset:9728
	ds_read_b64_tr_b16 v[238:239], v219 offset:13824
	v_mfma_f32_16x16x32_bf16 v[80:83], v[184:187], v[148:151], v[80:83]
	v_exp_f32_e32 v152, v152
	v_exp_f32_e32 v153, v153
	v_exp_f32_e32 v154, v154
	v_mfma_f32_16x16x32_bf16 v[80:83], v[176:179], v[164:167], v[80:83]
	v_exp_f32_e32 v155, v155
	v_mfma_f32_16x16x32_bf16 v[84:87], v[184:187], v[160:163], v[84:87]
	v_mfma_f32_16x16x32_bf16 v[84:87], v[176:179], v[168:171], v[84:87]
	ds_read_b64_tr_b16 v[176:177], v196 offset:1536
	ds_read_b64_tr_b16 v[178:179], v196 offset:5632
	ds_read_b64_tr_b16 v[184:185], v196 offset:9728
	ds_read_b64_tr_b16 v[186:187], v196 offset:13824
	v_mfma_f32_16x16x32_bf16 v[72:75], v[188:191], v[148:151], v[72:75]
	v_exp_f32_e32 v144, v144
	v_exp_f32_e32 v145, v145
	v_exp_f32_e32 v146, v146
	v_mfma_f32_16x16x32_bf16 v[72:75], v[180:183], v[164:167], v[72:75]
	v_exp_f32_e32 v147, v147
	v_mfma_f32_16x16x32_bf16 v[76:79], v[188:191], v[160:163], v[76:79]
	v_mfma_f32_16x16x32_bf16 v[76:79], v[180:183], v[168:171], v[76:79]
	s_waitcnt lgkmcnt(0)
	v_mfma_f32_16x16x32_bf16 v[64:67], v[192:195], v[148:151], v[64:67]
	v_exp_f32_e32 v156, v156
	v_exp_f32_e32 v157, v157
	v_exp_f32_e32 v158, v158
	v_mfma_f32_16x16x32_bf16 v[64:67], v[236:239], v[164:167], v[64:67]
	v_exp_f32_e32 v159, v159
	v_mfma_f32_16x16x32_bf16 v[68:71], v[192:195], v[160:163], v[68:71]
	v_mfma_f32_16x16x32_bf16 v[68:71], v[236:239], v[168:171], v[68:71]
	v_mfma_f32_16x16x32_bf16 v[56:59], v[176:179], v[148:151], v[56:59]
	v_exp_f32_e32 v148, v172
	v_exp_f32_e32 v149, v173
	v_exp_f32_e32 v150, v174
	v_mfma_f32_16x16x32_bf16 v[56:59], v[184:187], v[164:167], v[56:59]
	v_exp_f32_e32 v151, v175
	s_andn2_b64 vcc, exec, s[34:35]
	v_mfma_f32_16x16x32_bf16 v[60:63], v[176:179], v[160:163], v[60:63]
	v_mfma_f32_16x16x32_bf16 v[60:63], v[184:187], v[168:171], v[60:63]
	s_cbranch_vccnz .LBB0_969
	v_max_f32_e32 v160, v209, v209
	v_max_f32_e32 v161, v208, v208
	v_min_f32_e32 v160, v161, v160
	v_cmp_gt_f32_e32 vcc, 1.0, v160
	s_cbranch_vccz .LBB0_969
	v_pk_mul_f32 v[112:113], v[112:113], v[208:209] op_sel_hi:[1,0]
	v_pk_mul_f32 v[114:115], v[114:115], v[208:209] op_sel_hi:[1,0]
	v_pk_mul_f32 v[104:105], v[104:105], v[208:209] op_sel_hi:[1,0]
	v_pk_mul_f32 v[106:107], v[106:107], v[208:209] op_sel_hi:[1,0]
	v_pk_mul_f32 v[96:97], v[96:97], v[208:209] op_sel_hi:[1,0]
	v_pk_mul_f32 v[98:99], v[98:99], v[208:209] op_sel_hi:[1,0]
	v_pk_mul_f32 v[88:89], v[88:89], v[208:209] op_sel_hi:[1,0]
	v_pk_mul_f32 v[90:91], v[90:91], v[208:209] op_sel_hi:[1,0]
	v_pk_mul_f32 v[80:81], v[208:209], v[80:81] op_sel_hi:[0,1]
	v_pk_mul_f32 v[82:83], v[208:209], v[82:83] op_sel_hi:[0,1]
	v_pk_mul_f32 v[72:73], v[208:209], v[72:73] op_sel_hi:[0,1]
	v_pk_mul_f32 v[74:75], v[208:209], v[74:75] op_sel_hi:[0,1]
	v_pk_mul_f32 v[64:65], v[208:209], v[64:65] op_sel_hi:[0,1]
	v_pk_mul_f32 v[66:67], v[208:209], v[66:67] op_sel_hi:[0,1]
	v_pk_mul_f32 v[56:57], v[208:209], v[56:57] op_sel_hi:[0,1]
	v_pk_mul_f32 v[58:59], v[208:209], v[58:59] op_sel_hi:[0,1]
	v_pk_mul_f32 v[116:117], v[116:117], v[208:209] op_sel:[0,1]
	v_pk_mul_f32 v[118:119], v[118:119], v[208:209] op_sel:[0,1]
	v_pk_mul_f32 v[108:109], v[108:109], v[208:209] op_sel:[0,1]
	v_pk_mul_f32 v[110:111], v[110:111], v[208:209] op_sel:[0,1]
	v_pk_mul_f32 v[100:101], v[100:101], v[208:209] op_sel:[0,1]
	v_pk_mul_f32 v[102:103], v[102:103], v[208:209] op_sel:[0,1]
	v_pk_mul_f32 v[92:93], v[92:93], v[208:209] op_sel:[0,1]
	v_pk_mul_f32 v[94:95], v[94:95], v[208:209] op_sel:[0,1]
	v_pk_mul_f32 v[84:85], v[208:209], v[84:85] op_sel:[1,0]
	v_pk_mul_f32 v[86:87], v[208:209], v[86:87] op_sel:[1,0]
	v_pk_mul_f32 v[76:77], v[208:209], v[76:77] op_sel:[1,0]
	v_pk_mul_f32 v[78:79], v[208:209], v[78:79] op_sel:[1,0]
	v_pk_mul_f32 v[68:69], v[208:209], v[68:69] op_sel:[1,0]
	v_pk_mul_f32 v[70:71], v[208:209], v[70:71] op_sel:[1,0]
	v_pk_mul_f32 v[60:61], v[208:209], v[60:61] op_sel:[1,0]
	v_pk_mul_f32 v[62:63], v[208:209], v[62:63] op_sel:[1,0]

.LBB0_971:
	s_add_u32 s36, s36, 0x180000
	s_addc_u32 s37, s37, 0
	s_add_i32 s25, s48, s77
	s_mov_b32 m0, s25
	s_nop 0
	global_load_lds_dwordx4 v228, s[36:37]
	s_add_i32 m0, s25, 0x400
	s_nop 0
	global_load_lds_dwordx4 v231, s[36:37]
	ds_read_b128 v[246:249], v243 offset:12288
	s_waitcnt lgkmcnt(0)
	v_mfma_f32_16x16x32_bf16 v[164:167], v[192:195], v[0:3], v[164:167]
	v_exp_f32_e32 v210, v132
	v_exp_f32_e32 v211, v133
	v_add_f32_e32 v212, v156, v245
	v_mfma_f32_16x16x32_bf16 v[160:163], v[192:195], v[36:39], v[160:163]
	v_add_f32_e32 v213, v148, v244
	v_add_u32_e32 v243, s49, v233
	ds_read_b128 v[192:195], v243
	v_exp_f32_e32 v250, v134
	v_exp_f32_e32 v251, v135
	v_mfma_f32_16x16x32_bf16 v[132:135], v[188:191], v[0:3], v[180:183]
	v_add_f32_e32 v212, v157, v212
	v_add_f32_e32 v213, v149, v213
	v_mfma_f32_16x16x32_bf16 v[172:175], v[188:191], v[36:39], v[172:175]
	ds_read_b128 v[180:183], v243 offset:4096
	v_mfma_f32_16x16x32_bf16 v[176:179], v[184:187], v[0:3], v[176:179]
	v_exp_f32_e32 v215, v128
	v_exp_f32_e32 v214, v129
	v_add_f32_e32 v188, v158, v212
	v_mfma_f32_16x16x32_bf16 v[140:143], v[184:187], v[36:39], v[140:143]
	v_add_f32_e32 v189, v150, v213
	ds_read_b128 v[184:187], v243 offset:8192
	v_exp_f32_e32 v218, v130
	v_exp_f32_e32 v198, v131
	v_mfma_f32_16x16x32_bf16 v[128:131], v[246:249], v[0:3], v[168:171]
	v_add_f32_e32 v199, v159, v188
	v_add_f32_e32 v212, v151, v189
	v_mfma_f32_16x16x32_bf16 v[168:171], v[246:249], v[36:39], v[136:139]
	ds_read_b128 v[188:191], v243 offset:12288
	s_waitcnt lgkmcnt(0)
	v_mfma_f32_16x16x32_bf16 v[164:167], v[192:195], v[12:15], v[164:167]
	v_add_f32_e32 v137, v235, v199
	v_add_f32_e32 v138, v237, v212
	v_mfma_f32_16x16x32_bf16 v[160:163], v[192:195], v[28:31], v[160:163]
	v_cvt_pk_bf16_f32 v136, v152, v153
	v_add_u32_e32 v199, s49, v230
	ds_read_b128 v[192:195], v199
	v_add_f32_e32 v139, v236, v137
	v_add_f32_e32 v138, v238, v138
	v_mfma_f32_16x16x32_bf16 v[132:135], v[180:183], v[12:15], v[132:135]
	v_cvt_pk_bf16_f32 v137, v154, v155
	v_mfma_f32_16x16x32_bf16 v[152:155], v[180:183], v[28:31], v[172:175]
	s_nop 2
	ds_read_b128 v[172:175], v199 offset:4096
	v_mfma_f32_16x16x32_bf16 v[176:179], v[184:187], v[12:15], v[176:179]
	v_add_f32_e32 v139, v241, v139
	v_add_f32_e32 v212, v239, v138
	v_mfma_f32_16x16x32_bf16 v[140:143], v[184:187], v[28:31], v[140:143]
	v_cvt_pk_bf16_f32 v138, v156, v157
	ds_read_b128 v[180:183], v199 offset:8192
	v_add_f32_e32 v213, v242, v139
	v_add_f32_e32 v212, v240, v212
	v_mfma_f32_16x16x32_bf16 v[128:131], v[188:191], v[12:15], v[128:131]
	v_cvt_pk_bf16_f32 v139, v158, v159
	v_mfma_f32_16x16x32_bf16 v[156:159], v[188:191], v[28:31], v[168:171]
	s_nop 2
	ds_read_b128 v[168:171], v199 offset:12288
	s_waitcnt lgkmcnt(0)
	v_mfma_f32_16x16x32_bf16 v[164:167], v[192:195], v[8:11], v[164:167]
	v_mfma_f32_16x16x32_bf16 v[184:187], v[192:195], v[24:27], v[160:163]
	s_nop 2
	v_add_f32_e32 v161, v210, v213
	v_add_f32_e32 v162, v215, v212
	v_cvt_pk_bf16_f32 v160, v144, v145
	v_add_u32_e32 v192, s49, v226
	ds_read_b128 v[188:191], v192 offset:16384
	v_add_f32_e32 v163, v211, v161
	v_add_f32_e32 v162, v214, v162
	v_mfma_f32_16x16x32_bf16 v[132:135], v[172:175], v[8:11], v[132:135]
	v_cvt_pk_bf16_f32 v161, v146, v147
	v_mfma_f32_16x16x32_bf16 v[144:147], v[172:175], v[24:27], v[152:155]
	s_nop 2
	ds_read_b128 v[152:155], v192 offset:18432
	v_mfma_f32_16x16x32_bf16 v[172:175], v[180:183], v[8:11], v[176:179]
	v_add_f32_e32 v163, v250, v163
	v_add_f32_e32 v193, v218, v162
	v_mfma_f32_16x16x32_bf16 v[140:143], v[180:183], v[24:27], v[140:143]
	v_cvt_pk_bf16_f32 v162, v148, v149
	ds_read_b128 v[176:179], v192 offset:20480
	v_add_f32_e32 v194, v251, v163
	v_add_f32_e32 v195, v198, v193
	v_mfma_f32_16x16x32_bf16 v[128:131], v[168:171], v[8:11], v[128:131]
	v_cvt_pk_bf16_f32 v163, v150, v151
	v_mfma_f32_16x16x32_bf16 v[148:151], v[168:171], v[24:27], v[156:159]
	s_nop 2
	ds_read_b128 v[156:159], v192 offset:22528
	s_waitcnt lgkmcnt(0)
	v_mfma_f32_16x16x32_bf16 v[168:171], v[188:191], v[16:19], v[164:167]
	v_cvt_pk_bf16_f32 v164, v235, v236
	v_mfma_f32_16x16x32_bf16 v[180:183], v[188:191], v[32:35], v[184:187]
	v_add_u32_e32 v192, s49, v224
	s_nop 1
	ds_read_b128 v[184:187], v192 offset:16384
	v_mfma_f32_16x16x32_bf16 v[132:135], v[152:155], v[16:19], v[132:135]
	v_cvt_pk_bf16_f32 v165, v241, v242
	v_mfma_f32_16x16x32_bf16 v[188:191], v[152:155], v[32:35], v[144:147]
	ds_read_b128 v[242:245], v192 offset:18432
	v_mfma_f32_16x16x32_bf16 v[140:143], v[176:179], v[32:35], v[140:143]
	v_cvt_pk_bf16_f32 v166, v210, v211
	v_mfma_f32_16x16x32_bf16 v[246:249], v[176:179], v[16:19], v[172:175]
	ds_read_b128 v[176:179], v192 offset:20480
	v_mfma_f32_16x16x32_bf16 v[128:131], v[156:159], v[16:19], v[128:131]
	v_cvt_pk_bf16_f32 v167, v250, v251
	v_mfma_f32_16x16x32_bf16 v[250:253], v[156:159], v[32:35], v[148:151]
	ds_read_b128 v[210:213], v192 offset:22528
	s_waitcnt lgkmcnt(0)
	v_mfma_f32_16x16x32_bf16 v[156:159], v[184:187], v[20:23], v[168:171]
	v_cvt_pk_bf16_f32 v168, v237, v238
	v_mfma_f32_16x16x32_bf16 v[144:147], v[184:187], v[44:47], v[180:183]
	v_mfma_f32_16x16x32_bf16 v[152:155], v[242:245], v[20:23], v[132:135]
	v_cvt_pk_bf16_f32 v169, v239, v240
	v_mfma_f32_16x16x32_bf16 v[172:175], v[242:245], v[44:47], v[188:191]
	v_mfma_f32_16x16x32_bf16 v[148:151], v[176:179], v[20:23], v[246:249]
	v_cvt_pk_bf16_f32 v170, v215, v214
	v_mfma_f32_16x16x32_bf16 v[140:143], v[176:179], v[44:47], v[140:143]
	v_mfma_f32_16x16x32_bf16 v[132:135], v[210:213], v[20:23], v[128:131]
	v_cvt_pk_bf16_f32 v171, v218, v198
	v_mfma_f32_16x16x32_bf16 v[128:131], v[210:213], v[44:47], v[250:253]
	s_lshl_b32 s25, s5, 14
	s_add_i32 s25, s25, 0
	s_add_i32 s25, s25, 0x12000
	v_add_u32_e32 v235, s25, v222
	v_add_u32_e32 v236, s25, v223
	ds_read_b64_tr_b16 v[176:177], v235
	ds_read_b64_tr_b16 v[178:179], v235 offset:4096
	ds_read_b64_tr_b16 v[180:181], v235 offset:8192
	ds_read_b64_tr_b16 v[182:183], v235 offset:12288
	ds_read_b64_tr_b16 v[184:185], v236
	ds_read_b64_tr_b16 v[186:187], v236 offset:4096
	ds_read_b64_tr_b16 v[190:191], v236 offset:4608
	ds_read_b64_tr_b16 v[188:189], v236 offset:512
	ds_read_b64_tr_b16 v[210:211], v236 offset:8192
	ds_read_b64_tr_b16 v[212:213], v236 offset:12288
	ds_read_b64_tr_b16 v[240:241], v236 offset:12800
	ds_read_b64_tr_b16 v[238:239], v236 offset:8704
	s_waitcnt lgkmcnt(0)
	v_mfma_f32_16x16x32_bf16 v[112:115], v[184:187], v[136:139], v[112:115]
	v_mfma_f32_16x16x32_bf16 v[116:119], v[184:187], v[160:163], v[116:119]
	v_max_f32_e32 v184, v157, v157
	v_max_f32_e32 v185, v156, v156
	v_max_f32_e32 v184, v185, v184
	v_mfma_f32_16x16x32_bf16 v[112:115], v[210:213], v[164:167], v[112:115]
	v_max3_f32 v184, v184, v158, v159
	v_max3_f32 v184, v184, v152, v153
	v_max3_f32 v184, v184, v154, v155
	v_mfma_f32_16x16x32_bf16 v[116:119], v[210:213], v[168:171], v[116:119]
	ds_read_b64_tr_b16 v[210:211], v235 offset:512
	ds_read_b64_tr_b16 v[212:213], v235 offset:4608
	ds_read_b64_tr_b16 v[242:243], v235 offset:8704
	ds_read_b64_tr_b16 v[244:245], v235 offset:12800
	v_mfma_f32_16x16x32_bf16 v[104:107], v[176:179], v[136:139], v[104:107]
	v_mfma_f32_16x16x32_bf16 v[176:179], v[176:179], v[160:163], v[108:111]
	v_mfma_f32_16x16x32_bf16 v[108:111], v[180:183], v[164:167], v[104:107]
	s_nop 5
	v_max3_f32 v104, v184, v148, v149
	v_max3_f32 v104, v104, v150, v151
	v_max3_f32 v104, v104, v132, v133
	v_max3_f32 v193, v104, v134, v135
	v_mfma_f32_16x16x32_bf16 v[104:107], v[180:183], v[168:171], v[176:179]
	ds_read_b64_tr_b16 v[184:185], v236 offset:1024
	ds_read_b64_tr_b16 v[186:187], v236 offset:5120
	s_nop 0
	ds_read_b64_tr_b16 v[176:177], v236 offset:9216
	ds_read_b64_tr_b16 v[178:179], v236 offset:13312
	v_mfma_f32_16x16x32_bf16 v[96:99], v[188:191], v[136:139], v[96:99]
	v_max_f32_e32 v180, v145, v145
	v_max_f32_e32 v181, v144, v144
	v_max_f32_e32 v180, v181, v180
	v_mfma_f32_16x16x32_bf16 v[96:99], v[238:241], v[164:167], v[96:99]
	v_max3_f32 v180, v180, v146, v147
	v_max3_f32 v180, v180, v172, v173
	v_max3_f32 v192, v180, v174, v175
	v_mfma_f32_16x16x32_bf16 v[100:103], v[188:191], v[160:163], v[100:103]
	v_mfma_f32_16x16x32_bf16 v[100:103], v[238:241], v[168:171], v[100:103]
	ds_read_b64_tr_b16 v[188:189], v235 offset:1024
	ds_read_b64_tr_b16 v[190:191], v235 offset:5120
	ds_read_b64_tr_b16 v[180:181], v235 offset:9216
	ds_read_b64_tr_b16 v[182:183], v235 offset:13312
	s_waitcnt lgkmcnt(0)
	v_mfma_f32_16x16x32_bf16 v[88:91], v[210:213], v[136:139], v[88:91]
	v_mfma_f32_16x16x32_bf16 v[210:213], v[210:213], v[160:163], v[92:95]
	v_mfma_f32_16x16x32_bf16 v[92:95], v[242:245], v[164:167], v[88:91]
	s_nop 5
	v_max3_f32 v88, v192, v140, v141
	v_max3_f32 v88, v88, v142, v143
	v_max3_f32 v88, v88, v128, v129
	v_max3_f32 v237, v88, v130, v131
	v_mfma_f32_16x16x32_bf16 v[88:91], v[242:245], v[168:171], v[210:213]
	v_max_f32_e32 v192, v193, v237
	v_cmp_ge_f32_e32 vcc, s62, v192
	s_cmp_lg_u64 vcc, exec
	s_cselect_b64 s[36:37], -1, 0
	s_cmp_eq_u64 vcc, exec
	v_mov_b32_e32 v192, 1.0
	s_cbranch_scc1 .LBB0_973
	ds_bpermute_b32 v48, v220, v193
	v_max_f32_e32 v49, v193, v193
	v_max_f32_e32 v50, v237, v237
	s_waitcnt lgkmcnt(0)
	v_max_f32_e32 v48, v48, v48
	v_max_f32_e32 v48, v49, v48
	ds_bpermute_b32 v49, v221, v48
	s_waitcnt lgkmcnt(0)
	v_max3_f32 v48, v48, v49, 0
	ds_bpermute_b32 v49, v220, v237
	v_exp_f32_e64 v192, -v48
	v_sub_f32_e32 v156, v156, v48
	v_sub_f32_e32 v157, v157, v48
	v_sub_f32_e32 v158, v158, v48
	s_waitcnt lgkmcnt(0)
	v_max_f32_e32 v49, v49, v49
	v_max_f32_e32 v49, v50, v49
	ds_bpermute_b32 v50, v221, v49
	v_sub_f32_e32 v159, v159, v48
	v_sub_f32_e32 v152, v152, v48
	v_sub_f32_e32 v153, v153, v48
	v_sub_f32_e32 v154, v154, v48
	s_waitcnt lgkmcnt(0)
	v_max3_f32 v49, v49, v50, 0
	v_exp_f32_e64 v193, -v49
	v_pk_add_f32 v[202:203], v[202:203], v[48:49]
	v_sub_f32_e32 v155, v155, v48
	v_pk_add_f32 v[120:121], v[202:203], 0 neg_lo:[1,1] neg_hi:[1,1]
	v_xor_b32_e32 v124, 0x80000000, v203
	v_sub_f32_e32 v151, v151, v48
	v_sub_f32_e32 v150, v150, v48
	v_sub_f32_e32 v149, v149, v48
	v_sub_f32_e32 v148, v148, v48
	v_sub_f32_e32 v135, v135, v48
	v_sub_f32_e32 v134, v134, v48
	v_sub_f32_e32 v133, v133, v48
	v_sub_f32_e32 v132, v132, v48
	v_mov_b32_e32 v121, v120
	v_mov_b32_e32 v122, v120
	v_mov_b32_e32 v123, v120
	v_sub_f32_e32 v144, v144, v49
	v_sub_f32_e32 v145, v145, v49
	v_sub_f32_e32 v146, v146, v49
	v_sub_f32_e32 v147, v147, v49
	v_sub_f32_e32 v172, v172, v49
	v_sub_f32_e32 v173, v173, v49
	v_sub_f32_e32 v174, v174, v49
	v_sub_f32_e32 v175, v175, v49
	v_sub_f32_e32 v143, v143, v49
	v_sub_f32_e32 v142, v142, v49
	v_sub_f32_e32 v141, v141, v49
	v_sub_f32_e32 v140, v140, v49
	v_sub_f32_e32 v131, v131, v49
	v_sub_f32_e32 v130, v130, v49
	v_sub_f32_e32 v129, v129, v49
	v_sub_f32_e32 v128, v128, v49
	v_mov_b32_e32 v125, v124
	v_mov_b32_e32 v126, v124
	v_mov_b32_e32 v127, v124
	v_mov_b32_e32 v48, v120
	v_mov_b32_e32 v49, v120
	v_mov_b32_e32 v50, v120
	v_mov_b32_e32 v51, v120
	v_mov_b32_e32 v52, v124
	v_mov_b32_e32 v53, v124
	v_mov_b32_e32 v54, v124
	v_mov_b32_e32 v55, v124
	s_branch .LBB0_974

.LBB0_974:
	ds_read_b64_tr_b16 v[210:211], v236 offset:1536
	ds_read_b64_tr_b16 v[212:213], v236 offset:5632
	ds_read_b64_tr_b16 v[238:239], v236 offset:9728
	ds_read_b64_tr_b16 v[240:241], v236 offset:13824
	v_mfma_f32_16x16x32_bf16 v[80:83], v[184:187], v[136:139], v[80:83]
	v_exp_f32_e32 v156, v156
	v_exp_f32_e32 v157, v157
	v_exp_f32_e32 v158, v158
	v_mfma_f32_16x16x32_bf16 v[80:83], v[176:179], v[164:167], v[80:83]
	v_exp_f32_e32 v159, v159
	v_mfma_f32_16x16x32_bf16 v[84:87], v[184:187], v[160:163], v[84:87]
	v_mfma_f32_16x16x32_bf16 v[84:87], v[176:179], v[168:171], v[84:87]
	ds_read_b64_tr_b16 v[176:177], v235 offset:1536
	ds_read_b64_tr_b16 v[178:179], v235 offset:5632
	ds_read_b64_tr_b16 v[184:185], v235 offset:9728
	ds_read_b64_tr_b16 v[186:187], v235 offset:13824
	v_mfma_f32_16x16x32_bf16 v[72:75], v[188:191], v[136:139], v[72:75]
	v_exp_f32_e32 v144, v144
	v_exp_f32_e32 v145, v145
	v_exp_f32_e32 v146, v146
	v_mfma_f32_16x16x32_bf16 v[72:75], v[180:183], v[164:167], v[72:75]
	v_exp_f32_e32 v147, v147
	v_mfma_f32_16x16x32_bf16 v[76:79], v[188:191], v[160:163], v[76:79]
	v_mfma_f32_16x16x32_bf16 v[76:79], v[180:183], v[168:171], v[76:79]
	s_waitcnt lgkmcnt(0)
	v_mfma_f32_16x16x32_bf16 v[64:67], v[210:213], v[136:139], v[64:67]
	v_exp_f32_e32 v152, v152
	v_exp_f32_e32 v153, v153
	v_exp_f32_e32 v154, v154
	v_mfma_f32_16x16x32_bf16 v[64:67], v[238:241], v[164:167], v[64:67]
	v_exp_f32_e32 v155, v155
	v_mfma_f32_16x16x32_bf16 v[68:71], v[210:213], v[160:163], v[68:71]
	v_mfma_f32_16x16x32_bf16 v[68:71], v[238:241], v[168:171], v[68:71]
	v_mfma_f32_16x16x32_bf16 v[56:59], v[176:179], v[136:139], v[56:59]
	v_exp_f32_e32 v136, v172
	v_exp_f32_e32 v137, v173
	v_exp_f32_e32 v138, v174
	v_mfma_f32_16x16x32_bf16 v[56:59], v[184:187], v[164:167], v[56:59]
	v_exp_f32_e32 v139, v175
	s_andn2_b64 vcc, exec, s[36:37]
	v_mfma_f32_16x16x32_bf16 v[60:63], v[176:179], v[160:163], v[60:63]
	v_mfma_f32_16x16x32_bf16 v[60:63], v[184:187], v[168:171], v[60:63]
	s_cbranch_vccnz .LBB0_977
	v_max_f32_e32 v160, v193, v193
	v_max_f32_e32 v161, v192, v192
	v_min_f32_e32 v160, v161, v160
	v_cmp_gt_f32_e32 vcc, 1.0, v160
	s_cbranch_vccz .LBB0_977
	v_pk_mul_f32 v[112:113], v[112:113], v[192:193] op_sel_hi:[1,0]
	v_pk_mul_f32 v[114:115], v[114:115], v[192:193] op_sel_hi:[1,0]
	v_pk_mul_f32 v[108:109], v[108:109], v[192:193] op_sel_hi:[1,0]
	v_pk_mul_f32 v[110:111], v[110:111], v[192:193] op_sel_hi:[1,0]
	v_pk_mul_f32 v[96:97], v[96:97], v[192:193] op_sel_hi:[1,0]
	v_pk_mul_f32 v[98:99], v[98:99], v[192:193] op_sel_hi:[1,0]
	v_pk_mul_f32 v[92:93], v[92:93], v[192:193] op_sel_hi:[1,0]
	v_pk_mul_f32 v[94:95], v[94:95], v[192:193] op_sel_hi:[1,0]
	v_pk_mul_f32 v[80:81], v[192:193], v[80:81] op_sel_hi:[0,1]
	v_pk_mul_f32 v[82:83], v[192:193], v[82:83] op_sel_hi:[0,1]
	v_pk_mul_f32 v[72:73], v[192:193], v[72:73] op_sel_hi:[0,1]
	v_pk_mul_f32 v[74:75], v[192:193], v[74:75] op_sel_hi:[0,1]
	v_pk_mul_f32 v[64:65], v[192:193], v[64:65] op_sel_hi:[0,1]
	v_pk_mul_f32 v[66:67], v[192:193], v[66:67] op_sel_hi:[0,1]
	v_pk_mul_f32 v[56:57], v[192:193], v[56:57] op_sel_hi:[0,1]
	v_pk_mul_f32 v[58:59], v[192:193], v[58:59] op_sel_hi:[0,1]
	v_pk_mul_f32 v[116:117], v[116:117], v[192:193] op_sel:[0,1]
	v_pk_mul_f32 v[118:119], v[118:119], v[192:193] op_sel:[0,1]
	v_pk_mul_f32 v[104:105], v[104:105], v[192:193] op_sel:[0,1]
	v_pk_mul_f32 v[106:107], v[106:107], v[192:193] op_sel:[0,1]
	v_pk_mul_f32 v[100:101], v[100:101], v[192:193] op_sel:[0,1]
	v_pk_mul_f32 v[102:103], v[102:103], v[192:193] op_sel:[0,1]
	v_pk_mul_f32 v[88:89], v[88:89], v[192:193] op_sel:[0,1]
	v_pk_mul_f32 v[90:91], v[90:91], v[192:193] op_sel:[0,1]
	v_pk_mul_f32 v[84:85], v[192:193], v[84:85] op_sel:[1,0]
	v_pk_mul_f32 v[86:87], v[192:193], v[86:87] op_sel:[1,0]
	v_pk_mul_f32 v[76:77], v[192:193], v[76:77] op_sel:[1,0]
	v_pk_mul_f32 v[78:79], v[192:193], v[78:79] op_sel:[1,0]
	v_pk_mul_f32 v[68:69], v[192:193], v[68:69] op_sel:[1,0]
	v_pk_mul_f32 v[70:71], v[192:193], v[70:71] op_sel:[1,0]
	v_pk_mul_f32 v[60:61], v[192:193], v[60:61] op_sel:[1,0]
	v_pk_mul_f32 v[62:63], v[192:193], v[62:63] op_sel:[1,0]
